# stack: count loop + attn bfe nops + writelane mask build
# speedup vs baseline: 1.0125x; 1.0125x over previous
.LBB0_1546:
	v_mov_b32_e32 v0, 0
	v_mov_b32_e32 v1, 0
	v_cmp_ge_f32_e64 s[98:99], v200, v2
	s_nop 1
	v_writelane_b32 v0, s98, 0
	v_writelane_b32 v1, s99, 0
	s_cmp_lt_u32 s95, 2
	s_cbranch_scc1 .Lmk0_done
	v_cmp_ge_f32_e64 s[98:99], v201, v2
	s_nop 1
	v_writelane_b32 v0, s98, 1
	v_writelane_b32 v1, s99, 1
	s_cmp_lt_u32 s95, 4
	s_cbranch_scc1 .Lmk0_done
	v_cmp_ge_f32_e64 s[98:99], v202, v2
	s_nop 1
	v_writelane_b32 v0, s98, 2
	v_writelane_b32 v1, s99, 2
	s_cmp_lt_u32 s95, 6
	s_cbranch_scc1 .Lmk0_done
	v_cmp_ge_f32_e64 s[98:99], v112, v2
	s_nop 1
	v_writelane_b32 v0, s98, 3
	v_writelane_b32 v1, s99, 3
	s_cmp_lt_u32 s95, 8
	s_cbranch_scc1 .Lmk0_done
	v_cmp_ge_f32_e64 s[98:99], v113, v2
	s_nop 1
	v_writelane_b32 v0, s98, 4
	v_writelane_b32 v1, s99, 4
	s_cmp_lt_u32 s95, 10
	s_cbranch_scc1 .Lmk0_done
	v_cmp_ge_f32_e64 s[98:99], v114, v2
	s_nop 1
	v_writelane_b32 v0, s98, 5
	v_writelane_b32 v1, s99, 5
	s_cmp_lt_u32 s95, 12
	s_cbranch_scc1 .Lmk0_done
	v_cmp_ge_f32_e64 s[98:99], v115, v2
	s_nop 1
	v_writelane_b32 v0, s98, 6
	v_writelane_b32 v1, s99, 6
	s_cmp_lt_u32 s95, 14
	s_cbranch_scc1 .Lmk0_done
	v_cmp_ge_f32_e64 s[98:99], v116, v2
	s_nop 1
	v_writelane_b32 v0, s98, 7
	v_writelane_b32 v1, s99, 7
	s_cmp_lt_u32 s95, 16
	s_cbranch_scc1 .Lmk0_done
	v_cmp_ge_f32_e64 s[98:99], v117, v2
	v_cmp_ge_f32_e64 s[100:101], v118, v2
	v_cmp_ge_f32_e32 vcc, v119, v2
	v_writelane_b32 v0, s98, 8
	v_writelane_b32 v1, s99, 8
	v_cmp_ge_f32_e64 s[98:99], v205, v2
	v_writelane_b32 v0, s100, 9
	v_writelane_b32 v1, s101, 9
	v_cmp_ge_f32_e64 s[100:101], v206, v2
	v_writelane_b32 v0, vcc_lo, 10
	v_writelane_b32 v1, vcc_hi, 10
	v_cmp_ge_f32_e32 vcc, v207, v2
	v_writelane_b32 v0, s98, 11
	v_writelane_b32 v1, s99, 11
	v_cmp_ge_f32_e64 s[98:99], v208, v2
	v_writelane_b32 v0, s100, 12
	v_writelane_b32 v1, s101, 12
	v_cmp_ge_f32_e64 s[100:101], v209, v2
	v_writelane_b32 v0, vcc_lo, 13
	v_writelane_b32 v1, vcc_hi, 13
	v_writelane_b32 v0, s98, 14
	v_writelane_b32 v1, s99, 14
	v_writelane_b32 v0, s100, 15
	v_writelane_b32 v1, s101, 15
	s_cmp_lt_u32 s95, 32
	s_cbranch_scc1 .Lmk0_done
	v_cmp_ge_f32_e64 s[98:99], v210, v2
	v_cmp_ge_f32_e64 s[100:101], v211, v2
	v_cmp_ge_f32_e32 vcc, v212, v2
	v_writelane_b32 v0, s98, 16
	v_writelane_b32 v1, s99, 16
	v_cmp_ge_f32_e64 s[98:99], v213, v2
	v_writelane_b32 v0, s100, 17
	v_writelane_b32 v1, s101, 17
	v_cmp_ge_f32_e64 s[100:101], v214, v2
	v_writelane_b32 v0, vcc_lo, 18
	v_writelane_b32 v1, vcc_hi, 18
	v_cmp_ge_f32_e32 vcc, v216, v2
	v_writelane_b32 v0, s98, 19
	v_writelane_b32 v1, s99, 19
	v_cmp_ge_f32_e64 s[98:99], v217, v2
	v_writelane_b32 v0, s100, 20
	v_writelane_b32 v1, s101, 20
	v_cmp_ge_f32_e64 s[100:101], v218, v2
	v_writelane_b32 v0, vcc_lo, 21
	v_writelane_b32 v1, vcc_hi, 21
	v_writelane_b32 v0, s98, 22
	v_writelane_b32 v1, s99, 22
	v_writelane_b32 v0, s100, 23
	v_writelane_b32 v1, s101, 23
	s_cmp_lt_u32 s95, 48
	s_cbranch_scc1 .Lmk0_done
	v_cmp_ge_f32_e64 s[98:99], v219, v2
	v_cmp_ge_f32_e64 s[100:101], v220, v2
	v_cmp_ge_f32_e32 vcc, v221, v2
	v_writelane_b32 v0, s98, 24
	v_writelane_b32 v1, s99, 24
	v_cmp_ge_f32_e64 s[98:99], v222, v2
	v_writelane_b32 v0, s100, 25
	v_writelane_b32 v1, s101, 25
	v_cmp_ge_f32_e64 s[100:101], v223, v2
	v_writelane_b32 v0, vcc_lo, 26
	v_writelane_b32 v1, vcc_hi, 26
	v_cmp_ge_f32_e32 vcc, v224, v2
	v_writelane_b32 v0, s98, 27
	v_writelane_b32 v1, s99, 27
	v_cmp_ge_f32_e64 s[98:99], v225, v2
	v_writelane_b32 v0, s100, 28
	v_writelane_b32 v1, s101, 28
	v_cmp_ge_f32_e64 s[100:101], v226, v2
	v_writelane_b32 v0, vcc_lo, 29
	v_writelane_b32 v1, vcc_hi, 29
	v_writelane_b32 v0, s98, 30
	v_writelane_b32 v1, s99, 30
	v_writelane_b32 v0, s100, 31
	v_writelane_b32 v1, s101, 31
	s_cmp_lt_u32 s95, 64
	s_cbranch_scc1 .Lmk0_done
	v_cmp_ge_f32_e64 s[98:99], v227, v2
	v_cmp_ge_f32_e64 s[100:101], v228, v2
	v_cmp_ge_f32_e32 vcc, v229, v2
	v_writelane_b32 v0, s98, 32
	v_writelane_b32 v1, s99, 32
	v_cmp_ge_f32_e64 s[98:99], v230, v2
	v_writelane_b32 v0, s100, 33
	v_writelane_b32 v1, s101, 33
	v_cmp_ge_f32_e64 s[100:101], v231, v2
	v_writelane_b32 v0, vcc_lo, 34
	v_writelane_b32 v1, vcc_hi, 34
	v_cmp_ge_f32_e32 vcc, v232, v2
	v_writelane_b32 v0, s98, 35
	v_writelane_b32 v1, s99, 35
	v_cmp_ge_f32_e64 s[98:99], v233, v2
	v_writelane_b32 v0, s100, 36
	v_writelane_b32 v1, s101, 36
	v_cmp_ge_f32_e64 s[100:101], v234, v2
	v_writelane_b32 v0, vcc_lo, 37
	v_writelane_b32 v1, vcc_hi, 37
	v_writelane_b32 v0, s98, 38
	v_writelane_b32 v1, s99, 38
	v_writelane_b32 v0, s100, 39
	v_writelane_b32 v1, s101, 39
	s_cmpk_lt_u32 s95, 80
	s_cbranch_scc1 .Lmk0_done
	v_cmp_ge_f32_e64 s[98:99], v235, v2
	v_cmp_ge_f32_e64 s[100:101], v236, v2
	v_cmp_ge_f32_e32 vcc, v237, v2
	v_writelane_b32 v0, s98, 40
	v_writelane_b32 v1, s99, 40
	v_cmp_ge_f32_e64 s[98:99], v238, v2
	v_writelane_b32 v0, s100, 41
	v_writelane_b32 v1, s101, 41
	v_cmp_ge_f32_e64 s[100:101], v239, v2
	v_writelane_b32 v0, vcc_lo, 42
	v_writelane_b32 v1, vcc_hi, 42
	v_cmp_ge_f32_e32 vcc, v240, v2
	v_writelane_b32 v0, s98, 43
	v_writelane_b32 v1, s99, 43
	v_cmp_ge_f32_e64 s[98:99], v241, v2
	v_writelane_b32 v0, s100, 44
	v_writelane_b32 v1, s101, 44
	v_cmp_ge_f32_e64 s[100:101], v242, v2
	v_writelane_b32 v0, vcc_lo, 45
	v_writelane_b32 v1, vcc_hi, 45
	v_writelane_b32 v0, s98, 46
	v_writelane_b32 v1, s99, 46
	v_writelane_b32 v0, s100, 47
	v_writelane_b32 v1, s101, 47
	s_cmpk_lt_u32 s95, 96
	s_cbranch_scc1 .Lmk0_done
	v_cmp_ge_f32_e64 s[98:99], v243, v2
	v_cmp_ge_f32_e64 s[100:101], v244, v2
	v_cmp_ge_f32_e32 vcc, v245, v2
	v_writelane_b32 v0, s98, 48
	v_writelane_b32 v1, s99, 48
	v_cmp_ge_f32_e64 s[98:99], v246, v2
	v_writelane_b32 v0, s100, 49
	v_writelane_b32 v1, s101, 49
	v_cmp_ge_f32_e64 s[100:101], v247, v2
	v_writelane_b32 v0, vcc_lo, 50
	v_writelane_b32 v1, vcc_hi, 50
	v_cmp_ge_f32_e32 vcc, v248, v2
	v_writelane_b32 v0, s98, 51
	v_writelane_b32 v1, s99, 51
	v_cmp_ge_f32_e64 s[98:99], v249, v2
	v_writelane_b32 v0, s100, 52
	v_writelane_b32 v1, s101, 52
	v_cmp_ge_f32_e64 s[100:101], v250, v2
	v_writelane_b32 v0, vcc_lo, 53
	v_writelane_b32 v1, vcc_hi, 53
	v_writelane_b32 v0, s98, 54
	v_writelane_b32 v1, s99, 54
	v_writelane_b32 v0, s100, 55
	v_writelane_b32 v1, s101, 55
	s_cmpk_lt_u32 s95, 112
	s_cbranch_scc1 .Lmk0_done
	v_cmp_ge_f32_e64 s[98:99], v251, v2
	v_cmp_ge_f32_e64 s[100:101], v252, v2
	v_cmp_ge_f32_e32 vcc, v253, v2
	v_writelane_b32 v0, s98, 56
	v_writelane_b32 v1, s99, 56
	v_cmp_ge_f32_e64 s[98:99], v215, v2
	v_writelane_b32 v0, s100, 57
	v_writelane_b32 v1, s101, 57
	v_cmp_ge_f32_e64 s[100:101], v133, v2
	v_writelane_b32 v0, vcc_lo, 58
	v_writelane_b32 v1, vcc_hi, 58
	v_cmp_ge_f32_e32 vcc, v84, v2
	v_writelane_b32 v0, s98, 59
	v_writelane_b32 v1, s99, 59
	v_cmp_ge_f32_e64 s[98:99], v80, v2
	v_writelane_b32 v0, s100, 60
	v_writelane_b32 v1, s101, 60
	v_cmp_ge_f32_e64 s[100:101], v16, v2
	v_writelane_b32 v0, vcc_lo, 61
	v_writelane_b32 v1, vcc_hi, 61
	v_writelane_b32 v0, s98, 62
	v_writelane_b32 v1, s99, 62
	v_writelane_b32 v0, s100, 63
	v_writelane_b32 v1, s101, 63
.Lmk0_done:
	s_branch .LBB0_1134
.LBB0_1672:
	v_readlane_b32 s88, v254, 14
	v_readlane_b32 s0, v254, 0
	s_cmpk_lt_i32 s88, 0x100
	v_readlane_b32 s1, v254, 1
	s_cselect_b64 s[4:5], -1, 0
	s_cmpk_gt_i32 s88, 0xff
	v_readlane_b32 s89, v254, 15
	v_mbcnt_lo_u32_b32 v0, -1, 0
	v_mbcnt_hi_u32_b32 v0, -1, v0
	s_cbranch_scc1 .LBB0_1725
	s_load_dwordx2 s[10:11], s[0:1], 0x80
	v_readlane_b32 s0, v254, 3
	s_waitcnt vmcnt(0)
	v_and_b32_e32 v75, 31, v0
	s_movk_i32 s78, 0x90
	v_add_u32_e32 v64, s0, v0
	s_waitcnt lgkmcnt(0)
	s_add_u32 s6, s10, 0xa800000
	s_addc_u32 s7, s11, 0
	s_add_u32 s8, s10, 0x4200000
	s_addc_u32 s9, s11, 0
	v_and_b32_e32 v72, 0x7f, v64
	s_add_u32 s33, s10, 0xef00000
	v_ashrrev_i32_e32 v73, 7, v64
	s_addc_u32 s57, s11, 0
	s_add_i32 s0, 0, 0x24a00
	v_lshlrev_b32_e32 v1, 2, v72
	v_lshrrev_b32_e32 v0, 1, v0
	s_add_i32 s12, 0, 0x24800
	s_movk_i32 s2, 0x7f
	v_lshl_add_u32 v76, v64, 2, s0
	v_add_u32_e32 v77, s0, v1
	s_movk_i32 s0, 0x80
	v_mad_u32_u24 v2, v72, s78, 0
	v_lshlrev_b32_e32 v3, 5, v73
	v_and_b32_e32 v0, 16, v0
	s_add_u32 s10, s10, 0xff00000
	v_lshlrev_b32_e32 v74, 4, v73
	v_cmp_gt_u32_e64 s[0:1], s0, v64
	v_cmp_lt_u32_e64 s[2:3], s2, v64
	v_add_u32_e32 v78, s12, v1
	v_ashrrev_i32_e32 v65, 31, v64
	s_addc_u32 s11, s11, 0
	v_add_u32_e32 v79, s12, v0
	v_add_u32_e32 v80, 0, v0
	s_mov_b64 s[12:13], 0x10a00
	s_mov_b64 s[14:15], 0x10c00
	s_mov_b64 s[16:17], 0x10e00
	s_mov_b64 s[18:19], 0x11000
	s_mov_b64 s[20:21], 0x11200
	s_mov_b64 s[22:23], 0x11400
	s_mov_b64 s[24:25], 0x11600
	s_mov_b64 s[26:27], 0x11800
	s_mov_b64 s[28:29], 0x11a00
	s_mov_b64 s[30:31], 0x11c00
	s_mov_b64 s[34:35], 0x11e00
	s_mov_b64 s[36:37], 0x18000
	s_mov_b64 s[38:39], 0x18200
	s_mov_b64 s[40:41], 0x18400
	s_mov_b64 s[42:43], 0x18600
	s_mov_b64 s[44:45], 0x18800
	s_mov_b64 s[46:47], 0x18a00
	s_mov_b32 s79, 0x5040100
	s_movk_i32 s80, 0x4000
	s_movk_i32 s81, 0x2000
	v_mov_b32_e32 v67, 0
	v_add_u32_e32 v81, v2, v3
	s_mov_b32 s82, s88
	s_mov_b64 s[48:49], 0x18c00
	s_mov_b64 s[50:51], 0x18e00
	s_mov_b64 s[52:53], 0x19000
	s_mov_b64 s[54:55], 0x19200
	s_mov_b64 s[58:59], 0x19400
	s_mov_b64 s[60:61], 0x19600
	s_mov_b64 s[62:63], 0x19800
	s_mov_b64 s[64:65], 0x19a00
	s_mov_b64 s[66:67], 0x19c00
	s_mov_b64 s[68:69], 0x19e00
	s_branch .LBB0_1675

.LBB0_2149:
	v_mov_b32_e32 v0, 0
	v_mov_b32_e32 v1, 0
	v_cmp_ge_f32_e64 s[98:99], v200, v2
	s_nop 1
	v_writelane_b32 v0, s98, 0
	v_writelane_b32 v1, s99, 0
	s_cmp_lt_u32 s94, 2
	s_cbranch_scc1 .Lmk1_done
	v_cmp_ge_f32_e64 s[98:99], v201, v2
	s_nop 1
	v_writelane_b32 v0, s98, 1
	v_writelane_b32 v1, s99, 1
	s_cmp_lt_u32 s94, 4
	s_cbranch_scc1 .Lmk1_done
	v_cmp_ge_f32_e64 s[98:99], v202, v2
	s_nop 1
	v_writelane_b32 v0, s98, 2
	v_writelane_b32 v1, s99, 2
	s_cmp_lt_u32 s94, 6
	s_cbranch_scc1 .Lmk1_done
	v_cmp_ge_f32_e64 s[98:99], v112, v2
	s_nop 1
	v_writelane_b32 v0, s98, 3
	v_writelane_b32 v1, s99, 3
	s_cmp_lt_u32 s94, 8
	s_cbranch_scc1 .Lmk1_done
	v_cmp_ge_f32_e64 s[98:99], v113, v2
	s_nop 1
	v_writelane_b32 v0, s98, 4
	v_writelane_b32 v1, s99, 4
	s_cmp_lt_u32 s94, 10
	s_cbranch_scc1 .Lmk1_done
	v_cmp_ge_f32_e64 s[98:99], v114, v2
	s_nop 1
	v_writelane_b32 v0, s98, 5
	v_writelane_b32 v1, s99, 5
	s_cmp_lt_u32 s94, 12
	s_cbranch_scc1 .Lmk1_done
	v_cmp_ge_f32_e64 s[98:99], v115, v2
	s_nop 1
	v_writelane_b32 v0, s98, 6
	v_writelane_b32 v1, s99, 6
	s_cmp_lt_u32 s94, 14
	s_cbranch_scc1 .Lmk1_done
	v_cmp_ge_f32_e64 s[98:99], v116, v2
	s_nop 1
	v_writelane_b32 v0, s98, 7
	v_writelane_b32 v1, s99, 7
	s_cmp_lt_u32 s94, 16
	s_cbranch_scc1 .Lmk1_done
	v_cmp_ge_f32_e64 s[98:99], v117, v2
	v_cmp_ge_f32_e64 s[100:101], v118, v2
	v_cmp_ge_f32_e32 vcc, v119, v2
	v_writelane_b32 v0, s98, 8
	v_writelane_b32 v1, s99, 8
	v_cmp_ge_f32_e64 s[98:99], v205, v2
	v_writelane_b32 v0, s100, 9
	v_writelane_b32 v1, s101, 9
	v_cmp_ge_f32_e64 s[100:101], v206, v2
	v_writelane_b32 v0, vcc_lo, 10
	v_writelane_b32 v1, vcc_hi, 10
	v_cmp_ge_f32_e32 vcc, v207, v2
	v_writelane_b32 v0, s98, 11
	v_writelane_b32 v1, s99, 11
	v_cmp_ge_f32_e64 s[98:99], v208, v2
	v_writelane_b32 v0, s100, 12
	v_writelane_b32 v1, s101, 12
	v_cmp_ge_f32_e64 s[100:101], v209, v2
	v_writelane_b32 v0, vcc_lo, 13
	v_writelane_b32 v1, vcc_hi, 13
	v_writelane_b32 v0, s98, 14
	v_writelane_b32 v1, s99, 14
	v_writelane_b32 v0, s100, 15
	v_writelane_b32 v1, s101, 15
	s_cmp_lt_u32 s94, 32
	s_cbranch_scc1 .Lmk1_done
	v_cmp_ge_f32_e64 s[98:99], v210, v2
	v_cmp_ge_f32_e64 s[100:101], v211, v2
	v_cmp_ge_f32_e32 vcc, v212, v2
	v_writelane_b32 v0, s98, 16
	v_writelane_b32 v1, s99, 16
	v_cmp_ge_f32_e64 s[98:99], v213, v2
	v_writelane_b32 v0, s100, 17
	v_writelane_b32 v1, s101, 17
	v_cmp_ge_f32_e64 s[100:101], v214, v2
	v_writelane_b32 v0, vcc_lo, 18
	v_writelane_b32 v1, vcc_hi, 18
	v_cmp_ge_f32_e32 vcc, v216, v2
	v_writelane_b32 v0, s98, 19
	v_writelane_b32 v1, s99, 19
	v_cmp_ge_f32_e64 s[98:99], v217, v2
	v_writelane_b32 v0, s100, 20
	v_writelane_b32 v1, s101, 20
	v_cmp_ge_f32_e64 s[100:101], v218, v2
	v_writelane_b32 v0, vcc_lo, 21
	v_writelane_b32 v1, vcc_hi, 21
	v_writelane_b32 v0, s98, 22
	v_writelane_b32 v1, s99, 22
	v_writelane_b32 v0, s100, 23
	v_writelane_b32 v1, s101, 23
	s_cmp_lt_u32 s94, 48
	s_cbranch_scc1 .Lmk1_done
	v_cmp_ge_f32_e64 s[98:99], v219, v2
	v_cmp_ge_f32_e64 s[100:101], v220, v2
	v_cmp_ge_f32_e32 vcc, v221, v2
	v_writelane_b32 v0, s98, 24
	v_writelane_b32 v1, s99, 24
	v_cmp_ge_f32_e64 s[98:99], v222, v2
	v_writelane_b32 v0, s100, 25
	v_writelane_b32 v1, s101, 25
	v_cmp_ge_f32_e64 s[100:101], v223, v2
	v_writelane_b32 v0, vcc_lo, 26
	v_writelane_b32 v1, vcc_hi, 26
	v_cmp_ge_f32_e32 vcc, v224, v2
	v_writelane_b32 v0, s98, 27
	v_writelane_b32 v1, s99, 27
	v_cmp_ge_f32_e64 s[98:99], v225, v2
	v_writelane_b32 v0, s100, 28
	v_writelane_b32 v1, s101, 28
	v_cmp_ge_f32_e64 s[100:101], v226, v2
	v_writelane_b32 v0, vcc_lo, 29
	v_writelane_b32 v1, vcc_hi, 29
	v_writelane_b32 v0, s98, 30
	v_writelane_b32 v1, s99, 30
	v_writelane_b32 v0, s100, 31
	v_writelane_b32 v1, s101, 31
	s_cmp_lt_u32 s94, 64
	s_cbranch_scc1 .Lmk1_done
	v_cmp_ge_f32_e64 s[98:99], v227, v2
	v_cmp_ge_f32_e64 s[100:101], v228, v2
	v_cmp_ge_f32_e32 vcc, v229, v2
	v_writelane_b32 v0, s98, 32
	v_writelane_b32 v1, s99, 32
	v_cmp_ge_f32_e64 s[98:99], v230, v2
	v_writelane_b32 v0, s100, 33
	v_writelane_b32 v1, s101, 33
	v_cmp_ge_f32_e64 s[100:101], v231, v2
	v_writelane_b32 v0, vcc_lo, 34
	v_writelane_b32 v1, vcc_hi, 34
	v_cmp_ge_f32_e32 vcc, v232, v2
	v_writelane_b32 v0, s98, 35
	v_writelane_b32 v1, s99, 35
	v_cmp_ge_f32_e64 s[98:99], v233, v2
	v_writelane_b32 v0, s100, 36
	v_writelane_b32 v1, s101, 36
	v_cmp_ge_f32_e64 s[100:101], v234, v2
	v_writelane_b32 v0, vcc_lo, 37
	v_writelane_b32 v1, vcc_hi, 37
	v_writelane_b32 v0, s98, 38
	v_writelane_b32 v1, s99, 38
	v_writelane_b32 v0, s100, 39
	v_writelane_b32 v1, s101, 39
	s_cmpk_lt_u32 s94, 80
	s_cbranch_scc1 .Lmk1_done
	v_cmp_ge_f32_e64 s[98:99], v235, v2
	v_cmp_ge_f32_e64 s[100:101], v236, v2
	v_cmp_ge_f32_e32 vcc, v237, v2
	v_writelane_b32 v0, s98, 40
	v_writelane_b32 v1, s99, 40
	v_cmp_ge_f32_e64 s[98:99], v238, v2
	v_writelane_b32 v0, s100, 41
	v_writelane_b32 v1, s101, 41
	v_cmp_ge_f32_e64 s[100:101], v239, v2
	v_writelane_b32 v0, vcc_lo, 42
	v_writelane_b32 v1, vcc_hi, 42
	v_cmp_ge_f32_e32 vcc, v240, v2
	v_writelane_b32 v0, s98, 43
	v_writelane_b32 v1, s99, 43
	v_cmp_ge_f32_e64 s[98:99], v241, v2
	v_writelane_b32 v0, s100, 44
	v_writelane_b32 v1, s101, 44
	v_cmp_ge_f32_e64 s[100:101], v242, v2
	v_writelane_b32 v0, vcc_lo, 45
	v_writelane_b32 v1, vcc_hi, 45
	v_writelane_b32 v0, s98, 46
	v_writelane_b32 v1, s99, 46
	v_writelane_b32 v0, s100, 47
	v_writelane_b32 v1, s101, 47
	s_cmpk_lt_u32 s94, 96
	s_cbranch_scc1 .Lmk1_done
	v_cmp_ge_f32_e64 s[98:99], v243, v2
	v_cmp_ge_f32_e64 s[100:101], v244, v2
	v_cmp_ge_f32_e32 vcc, v245, v2
	v_writelane_b32 v0, s98, 48
	v_writelane_b32 v1, s99, 48
	v_cmp_ge_f32_e64 s[98:99], v246, v2
	v_writelane_b32 v0, s100, 49
	v_writelane_b32 v1, s101, 49
	v_cmp_ge_f32_e64 s[100:101], v247, v2
	v_writelane_b32 v0, vcc_lo, 50
	v_writelane_b32 v1, vcc_hi, 50
	v_cmp_ge_f32_e32 vcc, v248, v2
	v_writelane_b32 v0, s98, 51
	v_writelane_b32 v1, s99, 51
	v_cmp_ge_f32_e64 s[98:99], v249, v2
	v_writelane_b32 v0, s100, 52
	v_writelane_b32 v1, s101, 52
	v_cmp_ge_f32_e64 s[100:101], v250, v2
	v_writelane_b32 v0, vcc_lo, 53
	v_writelane_b32 v1, vcc_hi, 53
	v_writelane_b32 v0, s98, 54
	v_writelane_b32 v1, s99, 54
	v_writelane_b32 v0, s100, 55
	v_writelane_b32 v1, s101, 55
	s_cmpk_lt_u32 s94, 112
	s_cbranch_scc1 .Lmk1_done
	v_cmp_ge_f32_e64 s[98:99], v251, v2
	v_cmp_ge_f32_e64 s[100:101], v252, v2
	v_cmp_ge_f32_e32 vcc, v253, v2
	v_writelane_b32 v0, s98, 56
	v_writelane_b32 v1, s99, 56
	v_cmp_ge_f32_e64 s[98:99], v215, v2
	v_writelane_b32 v0, s100, 57
	v_writelane_b32 v1, s101, 57
	v_cmp_ge_f32_e64 s[100:101], v133, v2
	v_writelane_b32 v0, vcc_lo, 58
	v_writelane_b32 v1, vcc_hi, 58
	v_cmp_ge_f32_e32 vcc, v84, v2
	v_writelane_b32 v0, s98, 59
	v_writelane_b32 v1, s99, 59
	v_cmp_ge_f32_e64 s[98:99], v80, v2
	v_writelane_b32 v0, s100, 60
	v_writelane_b32 v1, s101, 60
	v_cmp_ge_f32_e64 s[100:101], v16, v2
	v_writelane_b32 v0, vcc_lo, 61
	v_writelane_b32 v1, vcc_hi, 61
	v_writelane_b32 v0, s98, 62
	v_writelane_b32 v1, s99, 62
	v_writelane_b32 v0, s100, 63
	v_writelane_b32 v1, s101, 63
.Lmk1_done:
	s_branch .LBB0_1737
.LBB0_2275:
	v_readlane_b32 s52, v255, 42
	v_readlane_b32 s53, v255, 43

.LBB0_2549:
	v_lshrrev_b32_e32 v92, v236, v204
	v_lshrrev_b32_e32 v93, v236, v205
	v_exp_f32_e32 v88, v131
	v_exp_f32_e32 v89, v130
	v_mfma_f32_32x32x16_bf16 v[64:79], v[162:165], v[198:201], v[64:79]
	v_bfe_i32 v90, v92, 0, 1
	v_bfe_i32 v91, v92, 1, 1
	v_and_b32_e32 v131, v91, v88
	v_and_b32_e32 v130, v90, v89
	v_exp_f32_e32 v88, v133
	v_exp_f32_e32 v89, v132
	v_bfe_i32 v90, v92, 2, 1
	v_bfe_i32 v91, v92, 3, 1
	v_and_b32_e32 v133, v91, v88
	v_and_b32_e32 v132, v90, v89
	s_nop 0
	v_exp_f32_e32 v88, v135
	v_exp_f32_e32 v89, v134
	s_waitcnt lgkmcnt(12)
	v_mfma_f32_32x32x16_bf16 v[32:47], v[162:165], v[194:197], v[32:47]
	v_bfe_i32 v90, v92, 8, 1
	v_bfe_i32 v91, v92, 9, 1
	v_and_b32_e32 v135, v91, v88
	v_and_b32_e32 v134, v90, v89
	v_exp_f32_e32 v88, v137
	v_exp_f32_e32 v89, v136
	v_bfe_i32 v90, v92, 10, 1
	v_bfe_i32 v91, v92, 11, 1
	v_and_b32_e32 v137, v91, v88
	v_and_b32_e32 v136, v90, v89
	v_add_u32_e32 v94, s25, v238
	ds_read_b128 v[88:91], v94
	ds_read_b128 v[174:177], v94 offset:512
	v_exp_f32_e32 v95, v139
	v_exp_f32_e32 v108, v138
	s_waitcnt lgkmcnt(12)
	v_mfma_f32_32x32x16_bf16 v[64:79], v[10:13], v[186:189], v[64:79]
	v_bfe_i32 v109, v92, 16, 1
	v_bfe_i32 v110, v92, 17, 1
	v_and_b32_e32 v139, v110, v95
	v_and_b32_e32 v138, v109, v108
	v_exp_f32_e32 v95, v141
	v_exp_f32_e32 v108, v140
	v_bfe_i32 v109, v92, 18, 1
	v_bfe_i32 v110, v92, 19, 1
	v_and_b32_e32 v141, v110, v95
	v_and_b32_e32 v140, v109, v108
	ds_read_b128 v[194:197], v94 offset:2048
	ds_read_b128 v[178:181], v94 offset:2560
	s_waitcnt lgkmcnt(12)
	v_mfma_f32_32x32x16_bf16 v[32:47], v[10:13], v[104:107], v[32:47]
	v_exp_f32_e32 v95, v143
	v_exp_f32_e32 v108, v142
	v_exp_f32_e32 v10, v145
	v_exp_f32_e32 v11, v144
	v_bfe_i32 v109, v92, 24, 1
	v_bfe_i32 v110, v92, 25, 1
	v_and_b32_e32 v143, v110, v95
	v_and_b32_e32 v142, v109, v108
	v_bfe_i32 v95, v92, 26, 1
	v_bfe_i32 v92, v92, 27, 1
	v_and_b32_e32 v145, v92, v10
	v_and_b32_e32 v144, v95, v11
	ds_read_b128 v[190:193], v94 offset:4096
	ds_read_b128 v[170:173], v94 offset:4608
	v_exp_f32_e32 v10, v115
	v_exp_f32_e32 v11, v114
	s_waitcnt lgkmcnt(12)
	v_mfma_f32_32x32x16_bf16 v[64:79], v[6:9], v[100:103], v[64:79]
	v_bfe_i32 v92, v93, 0, 1
	v_bfe_i32 v95, v93, 1, 1
	v_and_b32_e32 v115, v95, v10
	v_and_b32_e32 v114, v92, v11
	v_exp_f32_e32 v10, v117
	v_exp_f32_e32 v11, v116
	v_bfe_i32 v92, v93, 2, 1
	v_bfe_i32 v95, v93, 3, 1
	v_and_b32_e32 v117, v95, v10
	v_and_b32_e32 v116, v92, v11
	ds_read_b128 v[182:185], v94 offset:6144
	ds_read_b128 v[166:169], v94 offset:6656
	s_waitcnt lgkmcnt(12)
	v_mfma_f32_32x32x16_bf16 v[32:47], v[6:9], v[96:99], v[32:47]
	v_exp_f32_e32 v10, v119
	v_exp_f32_e32 v11, v118
	v_exp_f32_e32 v6, v121
	v_exp_f32_e32 v7, v120
	v_bfe_i32 v92, v93, 8, 1
	v_bfe_i32 v94, v93, 9, 1
	v_and_b32_e32 v119, v94, v10
	v_and_b32_e32 v118, v92, v11
	v_bfe_i32 v10, v93, 10, 1
	v_bfe_i32 v11, v93, 11, 1
	v_and_b32_e32 v121, v11, v6
	v_and_b32_e32 v120, v10, v7
	s_nop 0
	v_exp_f32_e32 v6, v123
	v_exp_f32_e32 v7, v122
	s_waitcnt lgkmcnt(10)
	v_mfma_f32_32x32x16_bf16 v[64:79], v[2:5], v[84:87], v[64:79]
	v_bfe_i32 v10, v93, 16, 1
	v_bfe_i32 v11, v93, 17, 1
	v_and_b32_e32 v123, v11, v6
	v_and_b32_e32 v122, v10, v7
	v_exp_f32_e32 v6, v125
	v_exp_f32_e32 v7, v124
	v_bfe_i32 v10, v93, 18, 1
	v_bfe_i32 v11, v93, 19, 1
	v_and_b32_e32 v125, v11, v6
	v_and_b32_e32 v124, v10, v7
	s_waitcnt lgkmcnt(8)
	v_mfma_f32_32x32x16_bf16 v[32:47], v[2:5], v[80:83], v[32:47]
	v_exp_f32_e32 v6, v127
	v_exp_f32_e32 v7, v126
	v_exp_f32_e32 v2, v129
	v_exp_f32_e32 v3, v128
	v_bfe_i32 v10, v93, 24, 1
	v_bfe_i32 v11, v93, 25, 1
	v_and_b32_e32 v127, v11, v6
	v_and_b32_e32 v126, v10, v7
	v_bfe_i32 v6, v93, 26, 1
	v_bfe_i32 v7, v93, 27, 1
	v_and_b32_e32 v129, v7, v2
	v_and_b32_e32 v128, v6, v3
	s_waitcnt vmcnt(2) lgkmcnt(0)
	s_barrier
	s_andn2_b64 vcc, exec, s[20:21]
	s_cbranch_vccnz .LBB0_2551
	s_waitcnt lgkmcnt(0)
	ds_read_b128 v[80:83], v227 offset:49248
	ds_read_b128 v[84:87], v227 offset:49216
	ds_read_b128 v[92:95], v227 offset:49184
	ds_read_b128 v[96:99], v227 offset:49152
	s_waitcnt lgkmcnt(3)
	v_pk_mul_f32 v[78:79], v[78:79], v[82:83]
	s_waitcnt lgkmcnt(2)
	v_pk_mul_f32 v[74:75], v[74:75], v[86:87]
	s_waitcnt lgkmcnt(1)
	v_pk_mul_f32 v[70:71], v[70:71], v[94:95]
	s_waitcnt lgkmcnt(0)
	v_pk_mul_f32 v[66:67], v[66:67], v[98:99]
	v_pk_mul_f32 v[76:77], v[76:77], v[80:81]
	v_pk_mul_f32 v[72:73], v[72:73], v[84:85]
	v_pk_mul_f32 v[68:69], v[68:69], v[92:93]
	v_pk_mul_f32 v[64:65], v[64:65], v[96:97]
	v_pk_mul_f32 v[46:47], v[46:47], v[82:83]
	v_pk_mul_f32 v[42:43], v[42:43], v[86:87]
	v_pk_mul_f32 v[38:39], v[38:39], v[94:95]
	v_pk_mul_f32 v[34:35], v[34:35], v[98:99]
	v_pk_mul_f32 v[44:45], v[44:45], v[80:81]
	v_pk_mul_f32 v[40:41], v[40:41], v[84:85]
	v_pk_mul_f32 v[36:37], v[36:37], v[92:93]
	v_pk_mul_f32 v[32:33], v[32:33], v[96:97]

.LBB0_2552:
	v_lshrrev_b32_e32 v0, v236, v204
	v_lshrrev_b32_e32 v14, v236, v205
	v_exp_f32_e32 v15, v97
	v_mfma_f32_32x32x16_bf16 v[64:79], v[162:165], v[198:201], v[64:79]
	v_bfe_i32 v97, v0, 1, 1
	v_exp_f32_e32 v96, v96
	v_and_b32_e32 v97, v97, v15
	v_exp_f32_e32 v15, v99
	v_exp_f32_e32 v98, v98
	v_bfe_i32 v122, v0, 0, 1
	v_bfe_i32 v99, v0, 3, 1
	v_and_b32_e32 v96, v122, v96
	v_bfe_i32 v122, v0, 2, 1
	v_and_b32_e32 v99, v99, v15
	v_and_b32_e32 v98, v122, v98
	s_nop 0
	v_exp_f32_e32 v15, v101
	s_waitcnt lgkmcnt(12)
	v_mfma_f32_32x32x16_bf16 v[32:47], v[162:165], v[186:189], v[32:47]
	v_bfe_i32 v101, v0, 9, 1
	v_exp_f32_e32 v100, v100
	v_and_b32_e32 v101, v101, v15
	v_exp_f32_e32 v15, v103
	v_exp_f32_e32 v102, v102
	v_bfe_i32 v122, v0, 8, 1
	v_bfe_i32 v103, v0, 11, 1
	v_and_b32_e32 v100, v122, v100
	v_bfe_i32 v122, v0, 10, 1
	v_and_b32_e32 v103, v103, v15
	v_and_b32_e32 v102, v122, v102
	v_add_u32_e32 v15, s46, v238
	ds_read_b128 v[194:197], v15
	ds_read_b128 v[186:189], v15 offset:512
	s_waitcnt lgkmcnt(12)
	v_mfma_f32_32x32x16_bf16 v[64:79], v[10:13], v[174:177], v[64:79]
	v_exp_f32_e32 v105, v105
	v_exp_f32_e32 v104, v104
	v_exp_f32_e32 v107, v107
	v_exp_f32_e32 v106, v106
	v_bfe_i32 v122, v0, 16, 1
	v_bfe_i32 v123, v0, 17, 1
	v_and_b32_e32 v105, v123, v105
	v_and_b32_e32 v104, v122, v104
	v_bfe_i32 v122, v0, 18, 1
	v_bfe_i32 v123, v0, 19, 1
	v_and_b32_e32 v107, v123, v107
	v_and_b32_e32 v106, v122, v106
	ds_read_b128 v[190:193], v15 offset:2048
	ds_read_b128 v[178:181], v15 offset:2560
	s_waitcnt lgkmcnt(12)
	v_mfma_f32_32x32x16_bf16 v[32:47], v[10:13], v[138:141], v[32:47]
	v_exp_f32_e32 v109, v109
	v_exp_f32_e32 v108, v108
	v_exp_f32_e32 v10, v111
	v_exp_f32_e32 v11, v110
	v_bfe_i32 v110, v0, 26, 1
	v_bfe_i32 v122, v0, 24, 1
	v_bfe_i32 v123, v0, 25, 1
	v_bfe_i32 v0, v0, 27, 1
	v_and_b32_e32 v109, v123, v109
	v_and_b32_e32 v108, v122, v108
	v_and_b32_e32 v111, v0, v10
	v_and_b32_e32 v110, v110, v11
	ds_read_b128 v[182:185], v15 offset:4096
	ds_read_b128 v[170:173], v15 offset:4608
	v_exp_f32_e32 v0, v81
	v_exp_f32_e32 v10, v80
	s_waitcnt lgkmcnt(12)
	v_mfma_f32_32x32x16_bf16 v[64:79], v[6:9], v[134:137], v[64:79]
	v_bfe_i32 v80, v14, 1, 1
	v_bfe_i32 v11, v14, 0, 1
	v_and_b32_e32 v81, v80, v0
	v_and_b32_e32 v80, v11, v10
	v_exp_f32_e32 v0, v83
	v_exp_f32_e32 v10, v82
	v_bfe_i32 v82, v14, 3, 1
	v_bfe_i32 v11, v14, 2, 1
	v_and_b32_e32 v83, v82, v0
	v_and_b32_e32 v82, v11, v10
	ds_read_b128 v[174:177], v15 offset:6144
	ds_read_b128 v[166:169], v15 offset:6656
	v_exp_f32_e32 v0, v85
	s_waitcnt lgkmcnt(12)
	v_mfma_f32_32x32x16_bf16 v[32:47], v[6:9], v[130:133], v[32:47]
	v_exp_f32_e32 v10, v84
	v_bfe_i32 v15, v14, 9, 1
	v_exp_f32_e32 v6, v86
	v_and_b32_e32 v85, v15, v0
	v_exp_f32_e32 v0, v87
	v_bfe_i32 v11, v14, 8, 1
	v_bfe_i32 v7, v14, 10, 1
	v_and_b32_e32 v84, v11, v10
	v_bfe_i32 v10, v14, 11, 1
	v_and_b32_e32 v86, v7, v6
	v_and_b32_e32 v87, v10, v0
	s_nop 0
	v_exp_f32_e32 v0, v89
	v_exp_f32_e32 v6, v88
	s_waitcnt lgkmcnt(10)
	v_mfma_f32_32x32x16_bf16 v[64:79], v[2:5], v[118:121], v[64:79]
	v_bfe_i32 v7, v14, 16, 1
	v_bfe_i32 v10, v14, 17, 1
	v_and_b32_e32 v89, v10, v0
	v_and_b32_e32 v88, v7, v6
	v_exp_f32_e32 v0, v91
	v_exp_f32_e32 v6, v90
	v_bfe_i32 v7, v14, 18, 1
	v_bfe_i32 v10, v14, 19, 1
	v_and_b32_e32 v91, v10, v0
	v_and_b32_e32 v90, v7, v6
	s_nop 0
	v_exp_f32_e32 v0, v93
	s_waitcnt lgkmcnt(8)
	v_mfma_f32_32x32x16_bf16 v[32:47], v[2:5], v[114:117], v[32:47]
	v_exp_f32_e32 v6, v92
	v_bfe_i32 v10, v14, 25, 1
	v_exp_f32_e32 v2, v94
	v_and_b32_e32 v93, v10, v0
	v_exp_f32_e32 v0, v95
	v_bfe_i32 v7, v14, 24, 1
	v_bfe_i32 v3, v14, 26, 1
	v_and_b32_e32 v92, v7, v6
	v_bfe_i32 v6, v14, 27, 1
	v_and_b32_e32 v94, v3, v2
	v_and_b32_e32 v95, v6, v0
	s_waitcnt vmcnt(2) lgkmcnt(0)
	s_barrier
	s_andn2_b64 vcc, exec, s[20:21]
	s_cbranch_vccnz .LBB0_2554
	s_waitcnt lgkmcnt(0)
	ds_read_b128 v[114:117], v227 offset:49248
	ds_read_b128 v[118:121], v227 offset:49216
	ds_read_b128 v[122:125], v227 offset:49184
	ds_read_b128 v[126:129], v227 offset:49152
	s_waitcnt lgkmcnt(3)
	v_pk_mul_f32 v[78:79], v[78:79], v[116:117]
	s_waitcnt lgkmcnt(2)
	v_pk_mul_f32 v[74:75], v[74:75], v[120:121]
	s_waitcnt lgkmcnt(1)
	v_pk_mul_f32 v[70:71], v[70:71], v[124:125]
	s_waitcnt lgkmcnt(0)
	v_pk_mul_f32 v[66:67], v[66:67], v[128:129]
	v_pk_mul_f32 v[76:77], v[76:77], v[114:115]
	v_pk_mul_f32 v[72:73], v[72:73], v[118:119]
	v_pk_mul_f32 v[68:69], v[68:69], v[122:123]
	v_pk_mul_f32 v[64:65], v[64:65], v[126:127]
	v_pk_mul_f32 v[46:47], v[46:47], v[116:117]
	v_pk_mul_f32 v[42:43], v[42:43], v[120:121]
	v_pk_mul_f32 v[38:39], v[38:39], v[124:125]
	v_pk_mul_f32 v[34:35], v[34:35], v[128:129]
	v_pk_mul_f32 v[44:45], v[44:45], v[114:115]
	v_pk_mul_f32 v[40:41], v[40:41], v[118:119]
	v_pk_mul_f32 v[36:37], v[36:37], v[122:123]
	v_pk_mul_f32 v[32:33], v[32:33], v[126:127]

.LBB0_2569:
	v_lshrrev_b32_e32 v88, v236, v206
	v_lshrrev_b32_e32 v89, v236, v207
	v_exp_f32_e32 v90, v131
	v_exp_f32_e32 v91, v130
	v_mfma_f32_32x32x16_bf16 v[64:79], v[162:165], v[202:205], v[64:79]
	v_bfe_i32 v92, v88, 0, 1
	v_bfe_i32 v93, v88, 1, 1
	v_and_b32_e32 v131, v93, v90
	v_and_b32_e32 v130, v92, v91
	v_exp_f32_e32 v90, v133
	v_exp_f32_e32 v91, v132
	v_bfe_i32 v92, v88, 2, 1
	v_bfe_i32 v93, v88, 3, 1
	v_and_b32_e32 v133, v93, v90
	v_and_b32_e32 v132, v92, v91
	s_nop 0
	v_exp_f32_e32 v90, v135
	v_exp_f32_e32 v91, v134
	s_waitcnt lgkmcnt(12)
	v_mfma_f32_32x32x16_bf16 v[32:47], v[162:165], v[194:197], v[32:47]
	v_bfe_i32 v92, v88, 8, 1
	v_bfe_i32 v93, v88, 9, 1
	v_and_b32_e32 v135, v93, v90
	v_and_b32_e32 v134, v92, v91
	v_exp_f32_e32 v90, v137
	v_exp_f32_e32 v91, v136
	v_bfe_i32 v92, v88, 10, 1
	v_bfe_i32 v93, v88, 11, 1
	v_and_b32_e32 v137, v93, v90
	v_and_b32_e32 v136, v92, v91
	v_add_u32_e32 v90, s47, v238
	ds_read_b128 v[194:197], v90
	ds_read_b128 v[186:189], v90 offset:512
	v_exp_f32_e32 v91, v139
	v_exp_f32_e32 v92, v138
	s_waitcnt lgkmcnt(12)
	v_mfma_f32_32x32x16_bf16 v[64:79], v[10:13], v[198:201], v[64:79]
	v_bfe_i32 v93, v88, 16, 1
	v_bfe_i32 v94, v88, 17, 1
	v_and_b32_e32 v139, v94, v91
	v_and_b32_e32 v138, v93, v92
	v_exp_f32_e32 v91, v141
	v_exp_f32_e32 v92, v140
	v_bfe_i32 v93, v88, 18, 1
	v_bfe_i32 v94, v88, 19, 1
	v_and_b32_e32 v141, v94, v91
	v_and_b32_e32 v140, v93, v92
	ds_read_b128 v[190:193], v90 offset:2048
	ds_read_b128 v[178:181], v90 offset:2560
	s_waitcnt lgkmcnt(12)
	v_mfma_f32_32x32x16_bf16 v[32:47], v[10:13], v[104:107], v[32:47]
	v_exp_f32_e32 v91, v143
	v_exp_f32_e32 v92, v142
	v_exp_f32_e32 v10, v145
	v_exp_f32_e32 v11, v144
	v_bfe_i32 v93, v88, 24, 1
	v_bfe_i32 v94, v88, 25, 1
	v_and_b32_e32 v143, v94, v91
	v_and_b32_e32 v142, v93, v92
	v_bfe_i32 v91, v88, 26, 1
	v_bfe_i32 v88, v88, 27, 1
	v_and_b32_e32 v145, v88, v10
	v_and_b32_e32 v144, v91, v11
	ds_read_b128 v[182:185], v90 offset:4096
	ds_read_b128 v[170:173], v90 offset:4608
	v_exp_f32_e32 v10, v115
	v_exp_f32_e32 v11, v114
	s_waitcnt lgkmcnt(12)
	v_mfma_f32_32x32x16_bf16 v[64:79], v[6:9], v[100:103], v[64:79]
	v_bfe_i32 v88, v89, 0, 1
	v_bfe_i32 v91, v89, 1, 1
	v_and_b32_e32 v115, v91, v10
	v_and_b32_e32 v114, v88, v11
	v_exp_f32_e32 v10, v117
	v_exp_f32_e32 v11, v116
	v_bfe_i32 v88, v89, 2, 1
	v_bfe_i32 v91, v89, 3, 1
	v_and_b32_e32 v117, v91, v10
	v_and_b32_e32 v116, v88, v11
	ds_read_b128 v[174:177], v90 offset:6144
	ds_read_b128 v[166:169], v90 offset:6656
	s_waitcnt lgkmcnt(12)
	v_mfma_f32_32x32x16_bf16 v[32:47], v[6:9], v[96:99], v[32:47]
	v_exp_f32_e32 v10, v119
	v_exp_f32_e32 v11, v118
	v_exp_f32_e32 v6, v121
	v_exp_f32_e32 v7, v120
	v_bfe_i32 v88, v89, 8, 1
	v_bfe_i32 v90, v89, 9, 1
	v_and_b32_e32 v119, v90, v10
	v_and_b32_e32 v118, v88, v11
	v_bfe_i32 v10, v89, 10, 1
	v_bfe_i32 v11, v89, 11, 1
	v_and_b32_e32 v121, v11, v6
	v_and_b32_e32 v120, v10, v7
	s_nop 0
	v_exp_f32_e32 v6, v123
	v_exp_f32_e32 v7, v122
	s_waitcnt lgkmcnt(10)
	v_mfma_f32_32x32x16_bf16 v[64:79], v[2:5], v[84:87], v[64:79]
	v_bfe_i32 v10, v89, 16, 1
	v_bfe_i32 v11, v89, 17, 1
	v_and_b32_e32 v123, v11, v6
	v_and_b32_e32 v122, v10, v7
	v_exp_f32_e32 v6, v125
	v_exp_f32_e32 v7, v124
	v_bfe_i32 v10, v89, 18, 1
	v_bfe_i32 v11, v89, 19, 1
	v_and_b32_e32 v125, v11, v6
	v_and_b32_e32 v124, v10, v7
	s_waitcnt lgkmcnt(8)
	v_mfma_f32_32x32x16_bf16 v[32:47], v[2:5], v[80:83], v[32:47]
	v_exp_f32_e32 v6, v127
	v_exp_f32_e32 v7, v126
	v_exp_f32_e32 v2, v129
	v_exp_f32_e32 v3, v128
	v_bfe_i32 v10, v89, 24, 1
	v_bfe_i32 v11, v89, 25, 1
	v_and_b32_e32 v127, v11, v6
	v_and_b32_e32 v126, v10, v7
	v_bfe_i32 v6, v89, 26, 1
	v_bfe_i32 v7, v89, 27, 1
	v_and_b32_e32 v129, v7, v2
	v_and_b32_e32 v128, v6, v3
	s_mov_b64 s[24:25], -1
	s_and_b64 vcc, exec, s[22:23]
	s_cbranch_vccz .LBB0_2600
	s_cmp_ge_u32 s26, s43
	s_cbranch_scc0 .LBB0_2572
	s_waitcnt vmcnt(0) lgkmcnt(0)
	s_barrier
	s_mov_b64 s[24:25], 0

.LBB0_2582:
	v_lshrrev_b32_e32 v14, v236, v234
	v_exp_f32_e32 v15, v97
	v_mfma_f32_32x32x16_bf16 v[64:79], v[162:165], v[206:209], v[64:79]
	v_bfe_i32 v97, v14, 1, 1
	v_exp_f32_e32 v96, v96
	v_and_b32_e32 v97, v97, v15
	v_exp_f32_e32 v15, v99
	v_exp_f32_e32 v98, v98
	v_bfe_i32 v113, v14, 0, 1
	v_bfe_i32 v99, v14, 3, 1
	v_and_b32_e32 v96, v113, v96
	v_bfe_i32 v113, v14, 2, 1
	v_and_b32_e32 v99, v99, v15
	v_and_b32_e32 v98, v113, v98
	s_nop 0
	v_exp_f32_e32 v15, v101
	s_waitcnt lgkmcnt(12)
	v_mfma_f32_32x32x16_bf16 v[32:47], v[162:165], v[202:205], v[32:47]
	v_bfe_i32 v101, v14, 9, 1
	v_exp_f32_e32 v100, v100
	v_and_b32_e32 v101, v101, v15
	v_exp_f32_e32 v15, v103
	v_exp_f32_e32 v102, v102
	v_bfe_i32 v113, v14, 8, 1
	v_bfe_i32 v103, v14, 11, 1
	v_and_b32_e32 v100, v113, v100
	v_bfe_i32 v113, v14, 10, 1
	v_and_b32_e32 v103, v103, v15
	v_and_b32_e32 v102, v113, v102
	v_cndmask_b32_e64 v15, 0, 1, s[28:29]
	v_cmp_ne_u32_e64 s[2:3], 1, v15
	s_andn2_b64 vcc, exec, s[28:29]
	v_add_u32_e32 v15, s46, v238
	s_cbranch_vccnz .LBB0_2584
	ds_read_b128 v[194:197], v15
	ds_read_b128 v[186:189], v15 offset:512
.LBB0_2584:
	s_waitcnt lgkmcnt(10)
	v_mfma_f32_32x32x16_bf16 v[64:79], v[10:13], v[198:201], v[64:79]
	v_exp_f32_e32 v105, v105
	v_exp_f32_e32 v104, v104
	v_exp_f32_e32 v107, v107
	v_exp_f32_e32 v106, v106
	v_bfe_i32 v113, v14, 16, 1
	v_bfe_i32 v122, v14, 17, 1
	v_and_b32_e32 v105, v122, v105
	v_and_b32_e32 v104, v113, v104
	v_bfe_i32 v113, v14, 18, 1
	v_bfe_i32 v122, v14, 19, 1
	v_and_b32_e32 v107, v122, v107
	v_and_b32_e32 v106, v113, v106
	s_and_b64 vcc, exec, s[2:3]
	s_cbranch_vccnz .LBB0_2586
	ds_read_b128 v[190:193], v15 offset:2048
	ds_read_b128 v[178:181], v15 offset:2560
.LBB0_2586:
	s_waitcnt lgkmcnt(8)
	v_mfma_f32_32x32x16_bf16 v[32:47], v[10:13], v[138:141], v[32:47]
	v_exp_f32_e32 v109, v109
	v_exp_f32_e32 v108, v108
	v_exp_f32_e32 v10, v111
	v_exp_f32_e32 v11, v110
	v_bfe_i32 v110, v14, 26, 1
	v_bfe_i32 v113, v14, 24, 1
	v_bfe_i32 v122, v14, 25, 1
	v_bfe_i32 v14, v14, 27, 1
	v_and_b32_e32 v109, v122, v109
	v_and_b32_e32 v108, v113, v108
	v_and_b32_e32 v111, v14, v10
	v_and_b32_e32 v110, v110, v11
	s_and_b64 vcc, exec, s[2:3]
	s_cbranch_vccnz .LBB0_2588
	ds_read_b128 v[182:185], v15 offset:4096
	ds_read_b128 v[170:173], v15 offset:4608
.LBB0_2588:
	v_exp_f32_e32 v11, v81
	v_exp_f32_e32 v14, v80
	s_waitcnt lgkmcnt(6)
	v_mfma_f32_32x32x16_bf16 v[64:79], v[6:9], v[134:137], v[64:79]
	v_lshrrev_b32_e32 v10, v236, v235
	v_bfe_i32 v80, v10, 0, 1
	v_bfe_i32 v81, v10, 1, 1
	v_and_b32_e32 v81, v81, v11
	v_and_b32_e32 v80, v80, v14
	v_exp_f32_e32 v11, v83
	v_exp_f32_e32 v14, v82
	v_bfe_i32 v82, v10, 2, 1
	v_bfe_i32 v83, v10, 3, 1
	v_and_b32_e32 v83, v83, v11
	v_and_b32_e32 v82, v82, v14
	s_and_b64 vcc, exec, s[2:3]
	s_cbranch_vccnz .LBB0_2590
	ds_read_b128 v[174:177], v15 offset:6144
	ds_read_b128 v[166:169], v15 offset:6656
.LBB0_2590:
	s_waitcnt lgkmcnt(4)
	v_mfma_f32_32x32x16_bf16 v[32:47], v[6:9], v[130:133], v[32:47]
	v_exp_f32_e32 v11, v85
	v_exp_f32_e32 v14, v84
	v_exp_f32_e32 v6, v87
	v_exp_f32_e32 v7, v86
	v_bfe_i32 v84, v10, 9, 1
	v_bfe_i32 v15, v10, 8, 1
	v_and_b32_e32 v85, v84, v11
	v_and_b32_e32 v84, v15, v14
	v_bfe_i32 v11, v10, 10, 1
	v_bfe_i32 v14, v10, 11, 1
	v_and_b32_e32 v87, v14, v6
	v_and_b32_e32 v86, v11, v7
	s_nop 0
	v_exp_f32_e32 v6, v89
	v_exp_f32_e32 v7, v88
	s_waitcnt lgkmcnt(2)
	v_mfma_f32_32x32x16_bf16 v[64:79], v[2:5], v[118:121], v[64:79]
	v_bfe_i32 v11, v10, 16, 1
	v_bfe_i32 v14, v10, 17, 1
	v_and_b32_e32 v89, v14, v6
	v_and_b32_e32 v88, v11, v7
	v_exp_f32_e32 v6, v91
	v_exp_f32_e32 v7, v90
	v_bfe_i32 v11, v10, 18, 1
	v_bfe_i32 v14, v10, 19, 1
	v_and_b32_e32 v91, v14, v6
	v_and_b32_e32 v90, v11, v7
	s_waitcnt lgkmcnt(0)
	v_mfma_f32_32x32x16_bf16 v[32:47], v[2:5], v[114:117], v[32:47]
	v_exp_f32_e32 v6, v93
	v_exp_f32_e32 v7, v92
	v_exp_f32_e32 v2, v95
	v_exp_f32_e32 v3, v94
	v_bfe_i32 v11, v10, 24, 1
	v_bfe_i32 v14, v10, 25, 1
	v_and_b32_e32 v93, v14, v6
	v_and_b32_e32 v92, v11, v7
	v_bfe_i32 v6, v10, 26, 1
	v_bfe_i32 v7, v10, 27, 1
	v_and_b32_e32 v95, v7, v2
	v_and_b32_e32 v94, v6, v3
	s_mov_b64 s[2:3], -1
	s_and_b64 vcc, exec, s[24:25]
	s_cbranch_vccz .LBB0_2602
	s_and_b64 vcc, exec, s[22:23]
	s_cbranch_vccz .LBB0_2593
	s_waitcnt vmcnt(0) lgkmcnt(0)
	s_barrier
	s_mov_b64 s[2:3], 0

.LBB0_2613:
	v_lshrrev_b32_e32 v14, v236, v14
	v_lshrrev_b32_e32 v15, v236, v15
	v_exp_f32_e32 v80, v115
	v_exp_f32_e32 v81, v114
	v_mfma_f32_32x32x16_bf16 v[64:79], v[162:165], v[142:145], v[64:79]
	v_bfe_i32 v82, v14, 0, 1
	v_bfe_i32 v83, v14, 1, 1
	v_and_b32_e32 v115, v83, v80
	v_and_b32_e32 v114, v82, v81
	v_exp_f32_e32 v80, v117
	v_exp_f32_e32 v81, v116
	v_bfe_i32 v82, v14, 2, 1
	v_bfe_i32 v83, v14, 3, 1
	v_and_b32_e32 v117, v83, v80
	v_and_b32_e32 v116, v82, v81
	s_nop 0
	v_exp_f32_e32 v80, v119
	v_exp_f32_e32 v81, v118
	s_waitcnt lgkmcnt(12)
	v_mfma_f32_32x32x16_bf16 v[32:47], v[162:165], v[138:141], v[32:47]
	v_bfe_i32 v82, v14, 8, 1
	v_bfe_i32 v83, v14, 9, 1
	v_and_b32_e32 v119, v83, v80
	v_and_b32_e32 v118, v82, v81
	v_exp_f32_e32 v80, v121
	v_exp_f32_e32 v81, v120
	v_bfe_i32 v82, v14, 10, 1
	v_bfe_i32 v83, v14, 11, 1
	v_and_b32_e32 v121, v83, v80
	v_and_b32_e32 v120, v82, v81
	s_nop 0
	v_exp_f32_e32 v80, v123
	v_exp_f32_e32 v81, v122
	s_waitcnt lgkmcnt(10)
	v_mfma_f32_32x32x16_bf16 v[64:79], v[10:13], v[134:137], v[64:79]
	v_bfe_i32 v82, v14, 16, 1
	v_bfe_i32 v83, v14, 17, 1
	v_and_b32_e32 v123, v83, v80
	v_and_b32_e32 v122, v82, v81
	v_exp_f32_e32 v80, v125
	v_exp_f32_e32 v81, v124
	v_bfe_i32 v82, v14, 18, 1
	v_bfe_i32 v83, v14, 19, 1
	v_and_b32_e32 v125, v83, v80
	v_and_b32_e32 v124, v82, v81
	s_waitcnt lgkmcnt(8)
	v_mfma_f32_32x32x16_bf16 v[32:47], v[10:13], v[130:133], v[32:47]
	v_exp_f32_e32 v80, v127
	v_exp_f32_e32 v81, v126
	v_exp_f32_e32 v10, v129
	v_exp_f32_e32 v11, v128
	v_bfe_i32 v82, v14, 24, 1
	v_bfe_i32 v83, v14, 25, 1
	v_bfe_i32 v12, v14, 26, 1
	v_bfe_i32 v13, v14, 27, 1
	v_and_b32_e32 v127, v83, v80
	v_and_b32_e32 v126, v82, v81
	v_and_b32_e32 v129, v13, v10
	v_and_b32_e32 v128, v12, v11
	v_exp_f32_e32 v10, v49
	v_exp_f32_e32 v11, v48
	s_waitcnt lgkmcnt(6)
	v_mfma_f32_32x32x16_bf16 v[64:79], v[6:9], v[108:111], v[64:79]
	v_bfe_i32 v12, v15, 0, 1
	v_bfe_i32 v13, v15, 1, 1
	v_and_b32_e32 v49, v13, v10
	v_and_b32_e32 v48, v12, v11
	v_exp_f32_e32 v10, v51
	v_exp_f32_e32 v11, v50
	v_bfe_i32 v12, v15, 2, 1
	v_bfe_i32 v13, v15, 3, 1
	v_and_b32_e32 v51, v13, v10
	v_and_b32_e32 v50, v12, v11
	s_waitcnt lgkmcnt(4)
	v_mfma_f32_32x32x16_bf16 v[32:47], v[6:9], v[104:107], v[32:47]
	v_exp_f32_e32 v10, v53
	v_exp_f32_e32 v11, v52
	v_exp_f32_e32 v6, v55
	v_exp_f32_e32 v7, v54
	v_bfe_i32 v12, v15, 8, 1
	v_bfe_i32 v13, v15, 9, 1
	v_bfe_i32 v8, v15, 10, 1
	v_bfe_i32 v9, v15, 11, 1
	v_and_b32_e32 v53, v13, v10
	v_and_b32_e32 v52, v12, v11
	v_and_b32_e32 v55, v9, v6
	v_and_b32_e32 v54, v8, v7
	s_nop 0
	v_exp_f32_e32 v6, v57
	v_exp_f32_e32 v7, v56
	s_waitcnt lgkmcnt(2)
	v_mfma_f32_32x32x16_bf16 v[64:79], v[2:5], v[100:103], v[64:79]
	v_bfe_i32 v8, v15, 16, 1
	v_bfe_i32 v9, v15, 17, 1
	v_and_b32_e32 v57, v9, v6
	v_and_b32_e32 v56, v8, v7
	v_exp_f32_e32 v6, v59
	v_exp_f32_e32 v7, v58
	v_bfe_i32 v8, v15, 18, 1
	v_bfe_i32 v9, v15, 19, 1
	v_and_b32_e32 v59, v9, v6
	v_and_b32_e32 v58, v8, v7
	s_waitcnt lgkmcnt(0)
	v_mfma_f32_32x32x16_bf16 v[32:47], v[2:5], v[96:99], v[32:47]
	v_exp_f32_e32 v6, v61
	v_exp_f32_e32 v7, v60
	v_exp_f32_e32 v2, v63
	v_exp_f32_e32 v3, v62
	v_bfe_i32 v8, v15, 24, 1
	v_bfe_i32 v9, v15, 25, 1
	v_bfe_i32 v4, v15, 26, 1
	v_bfe_i32 v5, v15, 27, 1
	v_and_b32_e32 v61, v9, v6
	v_and_b32_e32 v60, v8, v7
	v_and_b32_e32 v63, v5, v2
	v_and_b32_e32 v62, v4, v3
	s_andn2_b64 vcc, exec, s[2:3]
	s_cbranch_vccnz .LBB0_2615
	s_waitcnt lgkmcnt(0)
	ds_read_b128 v[2:5], v227 offset:49248
	ds_read_b128 v[6:9], v227 offset:49216
	ds_read_b128 v[10:13], v227 offset:49184
	ds_read_b128 v[80:83], v227 offset:49152
	s_waitcnt lgkmcnt(3)
	v_pk_mul_f32 v[78:79], v[78:79], v[4:5]
	s_waitcnt lgkmcnt(2)
	v_pk_mul_f32 v[74:75], v[74:75], v[8:9]
	s_waitcnt lgkmcnt(1)
	v_pk_mul_f32 v[70:71], v[70:71], v[12:13]
	s_waitcnt lgkmcnt(0)
	v_pk_mul_f32 v[66:67], v[66:67], v[82:83]
	v_pk_mul_f32 v[76:77], v[76:77], v[2:3]
	v_pk_mul_f32 v[72:73], v[72:73], v[6:7]
	v_pk_mul_f32 v[68:69], v[68:69], v[10:11]
	v_pk_mul_f32 v[64:65], v[64:65], v[80:81]
	v_pk_mul_f32 v[46:47], v[46:47], v[4:5]
	v_pk_mul_f32 v[42:43], v[42:43], v[8:9]
	v_pk_mul_f32 v[38:39], v[38:39], v[12:13]
	v_pk_mul_f32 v[34:35], v[34:35], v[82:83]
	v_pk_mul_f32 v[44:45], v[44:45], v[2:3]
	v_pk_mul_f32 v[40:41], v[40:41], v[6:7]
	v_pk_mul_f32 v[36:37], v[36:37], v[10:11]
	v_pk_mul_f32 v[32:33], v[32:33], v[80:81]

.LBB0_3147:
	v_lshrrev_b32_e32 v0, v236, v204
	v_lshrrev_b32_e32 v14, v236, v205
	v_exp_f32_e32 v15, v97
	v_mfma_f32_32x32x16_bf16 v[64:79], v[162:165], v[198:201], v[64:79]
	v_bfe_i32 v97, v0, 1, 1
	v_exp_f32_e32 v96, v96
	v_and_b32_e32 v97, v97, v15
	v_exp_f32_e32 v15, v99
	v_exp_f32_e32 v98, v98
	v_bfe_i32 v122, v0, 0, 1
	v_bfe_i32 v99, v0, 3, 1
	v_and_b32_e32 v96, v122, v96
	v_bfe_i32 v122, v0, 2, 1
	v_and_b32_e32 v99, v99, v15
	v_and_b32_e32 v98, v122, v98
	s_nop 0
	v_exp_f32_e32 v15, v101
	s_waitcnt lgkmcnt(12)
	v_mfma_f32_32x32x16_bf16 v[32:47], v[162:165], v[186:189], v[32:47]
	v_bfe_i32 v101, v0, 9, 1
	v_exp_f32_e32 v100, v100
	v_and_b32_e32 v101, v101, v15
	v_exp_f32_e32 v15, v103
	v_exp_f32_e32 v102, v102
	v_bfe_i32 v122, v0, 8, 1
	v_bfe_i32 v103, v0, 11, 1
	v_and_b32_e32 v100, v122, v100
	v_bfe_i32 v122, v0, 10, 1
	v_and_b32_e32 v103, v103, v15
	v_and_b32_e32 v102, v122, v102
	v_add_u32_e32 v15, s44, v238
	ds_read_b128 v[194:197], v15
	ds_read_b128 v[186:189], v15 offset:512
	s_waitcnt lgkmcnt(12)
	v_mfma_f32_32x32x16_bf16 v[64:79], v[10:13], v[174:177], v[64:79]
	v_exp_f32_e32 v105, v105
	v_exp_f32_e32 v104, v104
	v_exp_f32_e32 v107, v107
	v_exp_f32_e32 v106, v106
	v_bfe_i32 v122, v0, 16, 1
	v_bfe_i32 v123, v0, 17, 1
	v_and_b32_e32 v105, v123, v105
	v_and_b32_e32 v104, v122, v104
	v_bfe_i32 v122, v0, 18, 1
	v_bfe_i32 v123, v0, 19, 1
	v_and_b32_e32 v107, v123, v107
	v_and_b32_e32 v106, v122, v106
	ds_read_b128 v[190:193], v15 offset:2048
	ds_read_b128 v[178:181], v15 offset:2560
	s_waitcnt lgkmcnt(12)
	v_mfma_f32_32x32x16_bf16 v[32:47], v[10:13], v[138:141], v[32:47]
	v_exp_f32_e32 v109, v109
	v_exp_f32_e32 v108, v108
	v_exp_f32_e32 v10, v111
	v_exp_f32_e32 v11, v110
	v_bfe_i32 v110, v0, 26, 1
	v_bfe_i32 v122, v0, 24, 1
	v_bfe_i32 v123, v0, 25, 1
	v_bfe_i32 v0, v0, 27, 1
	v_and_b32_e32 v109, v123, v109
	v_and_b32_e32 v108, v122, v108
	v_and_b32_e32 v111, v0, v10
	v_and_b32_e32 v110, v110, v11
	ds_read_b128 v[182:185], v15 offset:4096
	ds_read_b128 v[170:173], v15 offset:4608
	v_exp_f32_e32 v0, v81
	v_exp_f32_e32 v10, v80
	s_waitcnt lgkmcnt(12)
	v_mfma_f32_32x32x16_bf16 v[64:79], v[6:9], v[134:137], v[64:79]
	v_bfe_i32 v80, v14, 1, 1
	v_bfe_i32 v11, v14, 0, 1
	v_and_b32_e32 v81, v80, v0
	v_and_b32_e32 v80, v11, v10
	v_exp_f32_e32 v0, v83
	v_exp_f32_e32 v10, v82
	v_bfe_i32 v82, v14, 3, 1
	v_bfe_i32 v11, v14, 2, 1
	v_and_b32_e32 v83, v82, v0
	v_and_b32_e32 v82, v11, v10
	ds_read_b128 v[174:177], v15 offset:6144
	ds_read_b128 v[166:169], v15 offset:6656
	v_exp_f32_e32 v0, v85
	s_waitcnt lgkmcnt(12)
	v_mfma_f32_32x32x16_bf16 v[32:47], v[6:9], v[130:133], v[32:47]
	v_exp_f32_e32 v10, v84
	v_bfe_i32 v15, v14, 9, 1
	v_exp_f32_e32 v6, v86
	v_and_b32_e32 v85, v15, v0
	v_exp_f32_e32 v0, v87
	v_bfe_i32 v11, v14, 8, 1
	v_bfe_i32 v7, v14, 10, 1
	v_and_b32_e32 v84, v11, v10
	v_bfe_i32 v10, v14, 11, 1
	v_and_b32_e32 v86, v7, v6
	v_and_b32_e32 v87, v10, v0
	s_nop 0
	v_exp_f32_e32 v0, v89
	v_exp_f32_e32 v6, v88
	s_waitcnt lgkmcnt(10)
	v_mfma_f32_32x32x16_bf16 v[64:79], v[2:5], v[118:121], v[64:79]
	v_bfe_i32 v7, v14, 16, 1
	v_bfe_i32 v10, v14, 17, 1
	v_and_b32_e32 v89, v10, v0
	v_and_b32_e32 v88, v7, v6
	v_exp_f32_e32 v0, v91
	v_exp_f32_e32 v6, v90
	v_bfe_i32 v7, v14, 18, 1
	v_bfe_i32 v10, v14, 19, 1
	v_and_b32_e32 v91, v10, v0
	v_and_b32_e32 v90, v7, v6
	s_nop 0
	v_exp_f32_e32 v0, v93
	s_waitcnt lgkmcnt(8)
	v_mfma_f32_32x32x16_bf16 v[32:47], v[2:5], v[114:117], v[32:47]
	v_exp_f32_e32 v6, v92
	v_bfe_i32 v10, v14, 25, 1
	v_exp_f32_e32 v2, v94
	v_and_b32_e32 v93, v10, v0
	v_exp_f32_e32 v0, v95
	v_bfe_i32 v7, v14, 24, 1
	v_bfe_i32 v3, v14, 26, 1
	v_and_b32_e32 v92, v7, v6
	v_bfe_i32 v6, v14, 27, 1
	v_and_b32_e32 v94, v3, v2
	v_and_b32_e32 v95, v6, v0
	s_waitcnt vmcnt(2) lgkmcnt(0)
	s_barrier
	s_andn2_b64 vcc, exec, s[20:21]
	s_cbranch_vccnz .LBB0_3149
	s_waitcnt lgkmcnt(0)
	ds_read_b128 v[114:117], v227 offset:49248
	ds_read_b128 v[118:121], v227 offset:49216
	ds_read_b128 v[122:125], v227 offset:49184
	ds_read_b128 v[126:129], v227 offset:49152
	s_waitcnt lgkmcnt(3)
	v_pk_mul_f32 v[78:79], v[78:79], v[116:117]
	s_waitcnt lgkmcnt(2)
	v_pk_mul_f32 v[74:75], v[74:75], v[120:121]
	s_waitcnt lgkmcnt(1)
	v_pk_mul_f32 v[70:71], v[70:71], v[124:125]
	s_waitcnt lgkmcnt(0)
	v_pk_mul_f32 v[66:67], v[66:67], v[128:129]
	v_pk_mul_f32 v[76:77], v[76:77], v[114:115]
	v_pk_mul_f32 v[72:73], v[72:73], v[118:119]
	v_pk_mul_f32 v[68:69], v[68:69], v[122:123]
	v_pk_mul_f32 v[64:65], v[64:65], v[126:127]
	v_pk_mul_f32 v[46:47], v[46:47], v[116:117]
	v_pk_mul_f32 v[42:43], v[42:43], v[120:121]
	v_pk_mul_f32 v[38:39], v[38:39], v[124:125]
	v_pk_mul_f32 v[34:35], v[34:35], v[128:129]
	v_pk_mul_f32 v[44:45], v[44:45], v[114:115]
	v_pk_mul_f32 v[40:41], v[40:41], v[118:119]
	v_pk_mul_f32 v[36:37], v[36:37], v[122:123]
	v_pk_mul_f32 v[32:33], v[32:33], v[126:127]

.LBB0_3164:
	v_lshrrev_b32_e32 v88, v236, v206
	v_lshrrev_b32_e32 v89, v236, v207
	v_exp_f32_e32 v90, v131
	v_exp_f32_e32 v91, v130
	v_mfma_f32_32x32x16_bf16 v[64:79], v[162:165], v[202:205], v[64:79]
	v_bfe_i32 v92, v88, 0, 1
	v_bfe_i32 v93, v88, 1, 1
	v_and_b32_e32 v131, v93, v90
	v_and_b32_e32 v130, v92, v91
	v_exp_f32_e32 v90, v133
	v_exp_f32_e32 v91, v132
	v_bfe_i32 v92, v88, 2, 1
	v_bfe_i32 v93, v88, 3, 1
	v_and_b32_e32 v133, v93, v90
	v_and_b32_e32 v132, v92, v91
	s_nop 0
	v_exp_f32_e32 v90, v135
	v_exp_f32_e32 v91, v134
	s_waitcnt lgkmcnt(12)
	v_mfma_f32_32x32x16_bf16 v[32:47], v[162:165], v[194:197], v[32:47]
	v_bfe_i32 v92, v88, 8, 1
	v_bfe_i32 v93, v88, 9, 1
	v_and_b32_e32 v135, v93, v90
	v_and_b32_e32 v134, v92, v91
	v_exp_f32_e32 v90, v137
	v_exp_f32_e32 v91, v136
	v_bfe_i32 v92, v88, 10, 1
	v_bfe_i32 v93, v88, 11, 1
	v_and_b32_e32 v137, v93, v90
	v_and_b32_e32 v136, v92, v91
	v_add_u32_e32 v90, s45, v238
	ds_read_b128 v[194:197], v90
	ds_read_b128 v[186:189], v90 offset:512
	v_exp_f32_e32 v91, v139
	v_exp_f32_e32 v92, v138
	s_waitcnt lgkmcnt(12)
	v_mfma_f32_32x32x16_bf16 v[64:79], v[10:13], v[198:201], v[64:79]
	v_bfe_i32 v93, v88, 16, 1
	v_bfe_i32 v94, v88, 17, 1
	v_and_b32_e32 v139, v94, v91
	v_and_b32_e32 v138, v93, v92
	v_exp_f32_e32 v91, v141
	v_exp_f32_e32 v92, v140
	v_bfe_i32 v93, v88, 18, 1
	v_bfe_i32 v94, v88, 19, 1
	v_and_b32_e32 v141, v94, v91
	v_and_b32_e32 v140, v93, v92
	ds_read_b128 v[190:193], v90 offset:2048
	ds_read_b128 v[178:181], v90 offset:2560
	s_waitcnt lgkmcnt(12)
	v_mfma_f32_32x32x16_bf16 v[32:47], v[10:13], v[104:107], v[32:47]
	v_exp_f32_e32 v91, v143
	v_exp_f32_e32 v92, v142
	v_exp_f32_e32 v10, v145
	v_exp_f32_e32 v11, v144
	v_bfe_i32 v93, v88, 24, 1
	v_bfe_i32 v94, v88, 25, 1
	v_and_b32_e32 v143, v94, v91
	v_and_b32_e32 v142, v93, v92
	v_bfe_i32 v91, v88, 26, 1
	v_bfe_i32 v88, v88, 27, 1
	v_and_b32_e32 v145, v88, v10
	v_and_b32_e32 v144, v91, v11
	ds_read_b128 v[182:185], v90 offset:4096
	ds_read_b128 v[170:173], v90 offset:4608
	v_exp_f32_e32 v10, v115
	v_exp_f32_e32 v11, v114
	s_waitcnt lgkmcnt(12)
	v_mfma_f32_32x32x16_bf16 v[64:79], v[6:9], v[100:103], v[64:79]
	v_bfe_i32 v88, v89, 0, 1
	v_bfe_i32 v91, v89, 1, 1
	v_and_b32_e32 v115, v91, v10
	v_and_b32_e32 v114, v88, v11
	v_exp_f32_e32 v10, v117
	v_exp_f32_e32 v11, v116
	v_bfe_i32 v88, v89, 2, 1
	v_bfe_i32 v91, v89, 3, 1
	v_and_b32_e32 v117, v91, v10
	v_and_b32_e32 v116, v88, v11
	ds_read_b128 v[174:177], v90 offset:6144
	ds_read_b128 v[166:169], v90 offset:6656
	s_waitcnt lgkmcnt(12)
	v_mfma_f32_32x32x16_bf16 v[32:47], v[6:9], v[96:99], v[32:47]
	v_exp_f32_e32 v10, v119
	v_exp_f32_e32 v11, v118
	v_exp_f32_e32 v6, v121
	v_exp_f32_e32 v7, v120
	v_bfe_i32 v88, v89, 8, 1
	v_bfe_i32 v90, v89, 9, 1
	v_and_b32_e32 v119, v90, v10
	v_and_b32_e32 v118, v88, v11
	v_bfe_i32 v10, v89, 10, 1
	v_bfe_i32 v11, v89, 11, 1
	v_and_b32_e32 v121, v11, v6
	v_and_b32_e32 v120, v10, v7
	s_nop 0
	v_exp_f32_e32 v6, v123
	v_exp_f32_e32 v7, v122
	s_waitcnt lgkmcnt(10)
	v_mfma_f32_32x32x16_bf16 v[64:79], v[2:5], v[84:87], v[64:79]
	v_bfe_i32 v10, v89, 16, 1
	v_bfe_i32 v11, v89, 17, 1
	v_and_b32_e32 v123, v11, v6
	v_and_b32_e32 v122, v10, v7
	v_exp_f32_e32 v6, v125
	v_exp_f32_e32 v7, v124
	v_bfe_i32 v10, v89, 18, 1
	v_bfe_i32 v11, v89, 19, 1
	v_and_b32_e32 v125, v11, v6
	v_and_b32_e32 v124, v10, v7
	s_waitcnt lgkmcnt(8)
	v_mfma_f32_32x32x16_bf16 v[32:47], v[2:5], v[80:83], v[32:47]
	v_exp_f32_e32 v6, v127
	v_exp_f32_e32 v7, v126
	v_exp_f32_e32 v2, v129
	v_exp_f32_e32 v3, v128
	v_bfe_i32 v10, v89, 24, 1
	v_bfe_i32 v11, v89, 25, 1
	v_and_b32_e32 v127, v11, v6
	v_and_b32_e32 v126, v10, v7
	v_bfe_i32 v6, v89, 26, 1
	v_bfe_i32 v7, v89, 27, 1
	v_and_b32_e32 v129, v7, v2
	v_and_b32_e32 v128, v6, v3
	s_mov_b64 s[24:25], -1
	s_and_b64 vcc, exec, s[22:23]
	s_cbranch_vccz .LBB0_3195
	s_cmp_ge_u32 s26, s43
	s_cbranch_scc0 .LBB0_3167
	s_waitcnt vmcnt(0) lgkmcnt(0)
	s_barrier
	s_mov_b64 s[24:25], 0

.LBB0_3177:
	v_lshrrev_b32_e32 v14, v236, v234
	v_exp_f32_e32 v15, v97
	v_mfma_f32_32x32x16_bf16 v[64:79], v[162:165], v[206:209], v[64:79]
	v_bfe_i32 v97, v14, 1, 1
	v_exp_f32_e32 v96, v96
	v_and_b32_e32 v97, v97, v15
	v_exp_f32_e32 v15, v99
	v_exp_f32_e32 v98, v98
	v_bfe_i32 v113, v14, 0, 1
	v_bfe_i32 v99, v14, 3, 1
	v_and_b32_e32 v96, v113, v96
	v_bfe_i32 v113, v14, 2, 1
	v_and_b32_e32 v99, v99, v15
	v_and_b32_e32 v98, v113, v98
	s_nop 0
	v_exp_f32_e32 v15, v101
	s_waitcnt lgkmcnt(12)
	v_mfma_f32_32x32x16_bf16 v[32:47], v[162:165], v[202:205], v[32:47]
	v_bfe_i32 v101, v14, 9, 1
	v_exp_f32_e32 v100, v100
	v_and_b32_e32 v101, v101, v15
	v_exp_f32_e32 v15, v103
	v_exp_f32_e32 v102, v102
	v_bfe_i32 v113, v14, 8, 1
	v_bfe_i32 v103, v14, 11, 1
	v_and_b32_e32 v100, v113, v100
	v_bfe_i32 v113, v14, 10, 1
	v_and_b32_e32 v103, v103, v15
	v_and_b32_e32 v102, v113, v102
	v_cndmask_b32_e64 v15, 0, 1, s[28:29]
	v_cmp_ne_u32_e64 s[2:3], 1, v15
	s_andn2_b64 vcc, exec, s[28:29]
	v_add_u32_e32 v15, s44, v238
	s_cbranch_vccnz .LBB0_3179
	ds_read_b128 v[194:197], v15
	ds_read_b128 v[186:189], v15 offset:512
